# out-proj phase offset: half the WGs (blockIdx bit5) convert the last 384 weight-queue grabs at P4 start instead of in P3a, so their residual epilogues overlap the other half's MFMA loops
# speedup vs baseline: 1.0035x; 1.0026x over previous
_Z10fwd_kernel4Args:
	v_writelane_b32 v254, s0, 31
	v_writelane_b32 v254, s1, 32
	s_load_dwordx8 s[76:83], s[0:1], 0xc0
	s_add_u32 s4, s0, 0xd8
	v_and_b32_e32 v193, 0x3ff, v0
	s_addc_u32 s5, s1, 0
	v_cmp_gt_u32_e32 vcc, 2, v193
	s_and_saveexec_b64 s[8:9], vcc
	v_lshl_add_u32 v1, v193, 2, 0
	v_add_u32_e32 v1, 0x23f80, v1
	v_mov_b32_e32 v2, 0
	ds_write_b32 v1, v2
	s_or_b64 exec, exec, s[8:9]
	s_load_dword s3, s[0:1], 0xe0
	s_waitcnt lgkmcnt(0)
	s_add_u32 s6, s78, 0x4000
	s_addc_u32 s7, s79, 0
	s_barrier
	v_writelane_b32 v254, s3, 0
	v_writelane_b32 v254, s6, 1
	s_getreg_b32 s3, hwreg(HW_REG_XCC_ID, 0, 4)
	s_and_b32 s3, s3, 15
	v_writelane_b32 v254, s7, 2
	v_cmp_eq_u32_e64 s[56:57], 0, v193
	v_writelane_b32 v254, s3, 3
	s_and_saveexec_b64 s[10:11], s[56:57]
	s_cbranch_execz .LBB0_5
	s_mov_b64 s[6:7], exec
	v_mbcnt_lo_u32_b32 v1, s6, 0
	v_mbcnt_hi_u32_b32 v1, s7, v1
	v_cmp_eq_u32_e32 vcc, 0, v1
	s_and_b64 s[8:9], exec, vcc
	s_mov_b64 exec, s[8:9]
	s_cbranch_execz .LBB0_5
	v_readlane_b32 s3, v254, 3
	s_bcnt1_i32_b64 s6, s[6:7]
	s_lshl_b32 s8, s3, 8
	v_mov_b32_e32 v2, s6
	v_readlane_b32 s6, v254, 1
	v_mov_b32_e32 v1, s8
	v_readlane_b32 s7, v254, 2
	s_nop 4
	global_atomic_add v1, v2, s[6:7] offset:1024

.LBB0_457:
	s_mov_b32 s98, 0
	s_cmpk_eq_i32 s82, 0x100
	s_cbranch_scc0 .LBB0_498
.Lwq_entry:
	s_movk_i32 s99, 0
	s_cmp_lg_u32 s98, 0
	s_cmovk_i32 s99, 0xf000
	s_movk_i32 s0, 0x4200
	v_mad_u32_u24 v0, v195, s0, 0
	v_lshrrev_b32_e32 v34, 5, v192
	v_lshl_add_u32 v3, v196, 2, v0
	s_movk_i32 s0, 0x84
	v_mad_u32_u24 v35, v34, s0, v3
	s_add_u32 s0, s78, 0x600000
	s_addc_u32 s1, s79, 0
	s_add_u32 s2, s78, 0x800000
	s_addc_u32 s3, s79, 0
	v_lshlrev_b32_e32 v4, 3, v193
	s_add_u32 s4, s78, 0x4800000
	v_lshrrev_b32_e32 v2, 3, v192
	v_and_b32_e32 v4, 56, v4
	s_addc_u32 s5, s79, 0
	v_mul_u32_u24_e32 v6, 0x84, v4
	v_lshlrev_b32_e32 v7, 2, v2
	v_lshlrev_b32_e32 v2, 10, v2
	s_add_u32 s6, s78, 0x200000
	v_lshl_add_u32 v32, v195, 1, s99
	v_mul_u32_u24_e32 v5, 0x84, v34
	v_add3_u32 v36, v0, v6, v7
	v_or_b32_e32 v6, 0x2000, v2
	v_or_b32_e32 v8, 0x4000, v2
	v_or_b32_e32 v10, 0x6000, v2
	s_addc_u32 s7, s79, 0
	s_add_i32 s11, 0, 0x222e0
	v_add_u32_e32 v33, 0x580, v32
	v_mov_b32_e32 v1, 0
	s_movk_i32 s10, 0x2000
	v_mov_b32_e32 v37, s11
	s_movk_i32 s24, 0x2cf
	s_cmp_lg_u32 s98, 0
	s_cmovk_i32 s24, 0x54f
	s_movk_i32 s25, 0x37f
	s_movk_i32 s30, 0x57f
	s_movk_i32 s31, 0x1fff
	s_mov_b64 s[8:9], 0x40000
	s_mov_b32 s33, 0x92492493
	v_lshlrev_b32_e32 v0, 2, v196
	v_add_u32_e32 v38, v3, v5
	v_lshlrev_b32_e32 v2, 1, v2
	v_lshlrev_b32_e32 v4, 1, v4
	v_lshlrev_b32_e32 v6, 1, v6
	v_lshlrev_b32_e32 v8, 1, v8
	v_lshlrev_b32_e32 v10, 1, v10
	s_branch .LBB0_461

.LBB0_498:
	s_cmp_lg_u32 s98, 0
	s_cbranch_scc1 .Lwq_ret
	s_waitcnt vmcnt(0)
	s_barrier
	s_and_saveexec_b64 s[0:1], s[56:57]
	v_readlane_b32 s30, v254, 5
	v_readlane_b32 s31, v254, 6
	s_cbranch_execz .LBB0_550
	s_add_i32 s2, 0, 0x23f80
	v_mov_b32_e32 v0, s2
	s_waitcnt vmcnt(0) expcnt(0) lgkmcnt(0)
	ds_read_b32 v2, v0
	s_add_i32 s2, 0, 0x23f84
	v_mov_b32_e32 v0, s2
	ds_read_b32 v0, v0
	s_waitcnt lgkmcnt(1)
	v_cmp_ne_u32_e32 vcc, 0, v2
	s_cbranch_vccnz .LBB0_514
	v_readlane_b32 s2, v254, 0
	s_mul_i32 s10, s83, s2
	s_add_u32 s2, s78, 0x4200
	s_addc_u32 s3, s79, 0
	s_add_u32 s4, s78, 0x4400
	s_addc_u32 s5, s79, 0
	s_add_u32 s6, s78, 0x4500
	s_addc_u32 s7, s79, 0
	s_add_u32 s8, s78, 0x4600
	s_addc_u32 s9, s79, 0
	s_add_u32 s12, s78, 0x4700
	s_addc_u32 s13, s79, 0
	s_add_u32 s14, s78, 0x4800
	s_addc_u32 s15, s79, 0
	s_add_u32 s16, s78, 0x4900
	s_addc_u32 s17, s79, 0
	s_add_u32 s18, s78, 0x4a00
	s_addc_u32 s19, s79, 0
	s_add_u32 s34, s78, 0x4b00
	s_addc_u32 s35, s79, 0
	s_add_u32 s36, s78, 0x4c00
	s_addc_u32 s37, s79, 0
	s_add_u32 s42, s78, 0x4d00
	s_addc_u32 s43, s79, 0
	s_add_u32 s46, s78, 0x4e00
	s_addc_u32 s47, s79, 0
	s_add_u32 s48, s78, 0x4f00
	s_addc_u32 s49, s79, 0
	s_add_u32 s50, s78, 0x5000
	s_addc_u32 s51, s79, 0
	s_add_u32 s52, s78, 0x5100
	s_addc_u32 s53, s79, 0
	s_add_u32 s54, s78, 0x5200
	s_addc_u32 s55, s79, 0
	s_add_u32 s58, s78, 0x5300
	s_mul_i32 s10, s10, s82
	s_addc_u32 s59, s79, 0
	s_mov_b32 s11, 1
	v_mov_b32_e32 v16, 0
	s_branch .LBB0_502

.LBB0_656:
	s_cmp_lt_i32 s80, 5
	s_cselect_b64 s[2:3], -1, 0
	s_and_b64 s[0:1], s[2:3], s[0:1]
	s_andn2_b64 vcc, exec, s[0:1]
	s_cbranch_vccnz .LBB0_681
	s_mov_b64 s[100:101], s[0:1]
	v_readlane_b32 s2, v254, 4
	s_bitcmp1_b32 s2, 5
	s_cbranch_scc0 .Lwq_ret
	s_cmpk_eq_i32 s82, 0x100
	s_cbranch_scc0 .Lwq_ret
	v_readlane_b32 s4, v254, 31
	v_readlane_b32 s5, v254, 32
	s_nop 4
	s_load_dwordx2 s[12:13], s[4:5], 0x40
	s_load_dwordx2 s[42:43], s[4:5], 0x98
	s_load_dwordx2 s[46:47], s[4:5], 0xa8
	s_load_dwordx4 s[48:51], s[4:5], 0xb0
	v_and_b32_e32 v196, 31, v193
	s_mov_b32 s98, 1
	s_waitcnt lgkmcnt(0)
	s_branch .Lwq_entry
.Lwq_ret:
	s_mov_b64 s[0:1], s[100:101]
	v_readlane_b32 s2, v254, 4
	s_cmpk_gt_i32 s2, 0x3ff
	v_readfirstlane_b32 s8, v193
	s_cbranch_scc1 .LBB0_681
	v_readlane_b32 s3, v254, 4
	s_ashr_i32 s33, s3, 31
	s_lshr_b32 s2, s33, 29
	s_add_i32 s5, s3, s2
	s_and_b32 s2, s5, -8
	s_sub_i32 s6, s3, s2
	s_cmp_gt_i32 s6, -1
	s_cbranch_scc0 .LBB0_660
	s_lshl_b32 s4, s6, 7
	s_cbranch_execz .LBB0_661
	s_branch .LBB0_662
